# G1 step 1 softplus: removed the log's denormal-rescale and non-finite fix-ups (its argument 1+exp2(-|x|c) is always in [1,2], so they are identities): 7 VALU per token
# speedup vs baseline: 1.0147x; 1.0019x over previous
.LBB0_1093:
	v_add_u32_e32 v129, 0, v127
	ds_read_b128 v[130:133], v129
	ds_read_b128 v[134:137], v129 offset:16
	ds_read_b128 v[138:141], v129 offset:32
	ds_read_b128 v[142:145], v129 offset:48
	v_add_u32_e32 v146, 0, v126
	s_waitcnt lgkmcnt(3)
	v_fma_f32 v130, v130, v98, v128
	v_fmac_f32_e32 v130, v131, v99
	v_fmac_f32_e32 v130, v132, v100
	v_fmac_f32_e32 v130, v133, v101
	s_waitcnt lgkmcnt(2)
	v_fmac_f32_e32 v130, v134, v102
	v_fmac_f32_e32 v130, v135, v103
	v_fmac_f32_e32 v130, v136, v104
	v_fmac_f32_e32 v130, v137, v105
	s_waitcnt lgkmcnt(1)
	v_fmac_f32_e32 v130, v138, v106
	v_fmac_f32_e32 v130, v139, v107
	v_fmac_f32_e32 v130, v140, v108
	v_fmac_f32_e32 v130, v141, v109
	s_waitcnt lgkmcnt(0)
	v_fmac_f32_e32 v130, v142, v110
	v_fmac_f32_e32 v130, v143, v111
	v_fmac_f32_e32 v130, v144, v112
	v_fmac_f32_e32 v130, v145, v113
	v_min_f32_e32 v131, 0, v130
	v_mul_f32_e64 v130, |v130|, s72
	v_exp_f32_e32 v130, v130
	v_add_u32_e32 v147, 0x10a00, v146
	v_add_u32_e32 v156, 0x10c04, v146
	v_add_u32_e32 v158, 0x10e08, v146
	v_add_f32_e32 v130, 1.0, v130
	s_add_i32 s9, s9, -4
	v_add_u32_e32 v126, 0x810, v126
	v_log_f32_e32 v130, v130
	s_nop 0
	v_add_u32_e32 v127, 0x100, v127
	v_add_u32_e32 v146, 0x1100c, v146
	v_mul_f32_e32 v133, 0x3f317217, v130
	v_fma_f32 v133, v130, s74, -v133
	v_fmac_f32_e32 v133, 0x3377d1cf, v130
	v_fmac_f32_e32 v133, 0x3f317217, v130
	s_cmp_eq_u32 s9, 0
	s_nop 0
	v_sub_f32_e32 v130, v131, v133
	v_fmac_f32_e32 v114, 0x3d800000, v130
	ds_write_b32 v147, v114
	ds_read_b128 v[130:133], v129 offset:64
	ds_read_b128 v[134:137], v129 offset:80
	ds_read_b128 v[138:141], v129 offset:96
	ds_read_b128 v[142:145], v129 offset:112
	s_waitcnt lgkmcnt(3)
	v_fma_f32 v130, v130, v98, v128
	v_fmac_f32_e32 v130, v131, v99
	v_fmac_f32_e32 v130, v132, v100
	v_fmac_f32_e32 v130, v133, v101
	s_waitcnt lgkmcnt(2)
	v_fmac_f32_e32 v130, v134, v102
	v_fmac_f32_e32 v130, v135, v103
	v_fmac_f32_e32 v130, v136, v104
	v_fmac_f32_e32 v130, v137, v105
	s_waitcnt lgkmcnt(1)
	v_fmac_f32_e32 v130, v138, v106
	v_fmac_f32_e32 v130, v139, v107
	v_fmac_f32_e32 v130, v140, v108
	v_fmac_f32_e32 v130, v141, v109
	s_waitcnt lgkmcnt(0)
	v_fmac_f32_e32 v130, v142, v110
	v_fmac_f32_e32 v130, v143, v111
	v_fmac_f32_e32 v130, v144, v112
	v_fmac_f32_e32 v130, v145, v113
	v_min_f32_e32 v131, 0, v130
	v_mul_f32_e64 v130, |v130|, s72
	v_exp_f32_e32 v130, v130
	s_nop 0
	v_add_f32_e32 v130, 1.0, v130
	s_nop 1
	v_log_f32_e32 v130, v130
	s_nop 0
	v_mul_f32_e32 v133, 0x3f317217, v130
	v_fma_f32 v133, v130, s74, -v133
	v_fmac_f32_e32 v133, 0x3377d1cf, v130
	v_fmac_f32_e32 v133, 0x3f317217, v130
	s_nop 1
	v_sub_f32_e32 v130, v131, v133
	v_fmac_f32_e32 v114, 0x3d800000, v130
	ds_write_b32 v156, v114
	ds_read_b128 v[130:133], v129 offset:128
	ds_read_b128 v[134:137], v129 offset:144
	ds_read_b128 v[138:141], v129 offset:160
	ds_read_b128 v[142:145], v129 offset:176
	s_waitcnt lgkmcnt(3)
	v_fma_f32 v130, v130, v98, v128
	v_fmac_f32_e32 v130, v131, v99
	v_fmac_f32_e32 v130, v132, v100
	v_fmac_f32_e32 v130, v133, v101
	s_waitcnt lgkmcnt(2)
	v_fmac_f32_e32 v130, v134, v102
	v_fmac_f32_e32 v130, v135, v103
	v_fmac_f32_e32 v130, v136, v104
	v_fmac_f32_e32 v130, v137, v105
	s_waitcnt lgkmcnt(1)
	v_fmac_f32_e32 v130, v138, v106
	v_fmac_f32_e32 v130, v139, v107
	v_fmac_f32_e32 v130, v140, v108
	v_fmac_f32_e32 v130, v141, v109
	s_waitcnt lgkmcnt(0)
	v_fmac_f32_e32 v130, v142, v110
	v_fmac_f32_e32 v130, v143, v111
	v_fmac_f32_e32 v130, v144, v112
	v_fmac_f32_e32 v130, v145, v113
	v_min_f32_e32 v131, 0, v130
	v_mul_f32_e64 v130, |v130|, s72
	v_exp_f32_e32 v130, v130
	s_nop 0
	v_add_f32_e32 v130, 1.0, v130
	s_nop 1
	v_log_f32_e32 v130, v130
	s_nop 0
	v_mul_f32_e32 v133, 0x3f317217, v130
	v_fma_f32 v133, v130, s74, -v133
	v_fmac_f32_e32 v133, 0x3377d1cf, v130
	v_fmac_f32_e32 v133, 0x3f317217, v130
	s_nop 1
	v_sub_f32_e32 v130, v131, v133
	v_fmac_f32_e32 v114, 0x3d800000, v130
	ds_write_b32 v158, v114
	ds_read_b128 v[130:133], v129 offset:192
	ds_read_b128 v[134:137], v129 offset:208
	ds_read_b128 v[138:141], v129 offset:224
	ds_read_b128 v[142:145], v129 offset:240
	s_waitcnt lgkmcnt(3)
	v_fma_f32 v129, v130, v98, v128
	v_fmac_f32_e32 v129, v131, v99
	v_fmac_f32_e32 v129, v132, v100
	v_fmac_f32_e32 v129, v133, v101
	s_waitcnt lgkmcnt(2)
	v_fmac_f32_e32 v129, v134, v102
	v_fmac_f32_e32 v129, v135, v103
	v_fmac_f32_e32 v129, v136, v104
	v_fmac_f32_e32 v129, v137, v105
	s_waitcnt lgkmcnt(1)
	v_fmac_f32_e32 v129, v138, v106
	v_fmac_f32_e32 v129, v139, v107
	v_fmac_f32_e32 v129, v140, v108
	v_fmac_f32_e32 v129, v141, v109
	s_waitcnt lgkmcnt(0)
	v_fmac_f32_e32 v129, v142, v110
	v_fmac_f32_e32 v129, v143, v111
	v_fmac_f32_e32 v129, v144, v112
	v_fmac_f32_e32 v129, v145, v113
	v_mul_f32_e64 v130, |v129|, s72
	v_exp_f32_e32 v130, v130
	v_min_f32_e32 v129, 0, v129
	v_add_f32_e32 v130, 1.0, v130
	s_nop 1
	v_log_f32_e32 v130, v130
	s_nop 0
	v_mul_f32_e32 v132, 0x3f317217, v130
	v_fma_f32 v132, v130, s74, -v132
	v_fmac_f32_e32 v132, 0x3377d1cf, v130
	v_fmac_f32_e32 v132, 0x3f317217, v130
	s_nop 1
	v_sub_f32_e32 v129, v129, v132
	v_fmac_f32_e32 v114, 0x3d800000, v129
	ds_write_b32 v146, v114
	s_cbranch_scc0 .LBB0_1093
	s_or_b32 s48, s8, s45
	v_bfe_u32 v158, v124, 5, 1
	s_ashr_i32 s50, s17, 6
	s_ashr_i32 s49, s48, 31
	v_lshl_or_b32 v160, s50, 1, v158
	s_lshl_b64 s[68:69], s[48:49], 4
	v_lshrrev_b32_e32 v98, 1, v124
	v_and_or_b32 v98, v98, 8, s68
	v_mov_b32_e32 v99, s69
	s_ashr_i32 s51, s50, 31
	v_lshlrev_b32_e32 v184, 5, v160
	v_lshl_add_u32 v159, v124, 2, s76
	v_lshl_add_u64 v[98:99], v[98:99], 0, s[50:51]
	v_add_u32_e32 v111, s76, v184
	ds_write_b32 v159, v114
	s_waitcnt lgkmcnt(0)
	s_barrier
	v_lshlrev_b64 v[102:103], 10, v[98:99]
	ds_read_b128 v[104:107], v111
	ds_read_b128 v[98:101], v111 offset:16
	ds_read_b128 v[128:131], v111 offset:512
	ds_read_b128 v[132:135], v111 offset:1024
	ds_read_b128 v[136:139], v111 offset:1536
	v_and_b32_e32 v156, 31, v124
	v_mul_u32_u24_e32 v110, 0x408, v156
	s_add_i32 s18, 0, 0x10a00
	v_cmp_gt_u32_e64 s[0:1], 8, v156
	s_waitcnt lgkmcnt(2)
	v_add_f32_e32 v126, v104, v128
	v_and_b32_e32 v108, 24, v124
	v_cndmask_b32_e64 v109, v104, 0, s[0:1]
	v_add3_u32 v104, s18, v110, v184
	ds_read2_b64 v[142:145], v104 offset1:1
	ds_read2_b64 v[178:181], v104 offset0:2 offset1:3
	v_cmp_lt_u32_e64 s[8:9], 15, v156
	v_cmp_eq_u32_e64 s[10:11], 24, v108
	s_waitcnt lgkmcnt(3)
	v_mov_b32_e32 v108, v132
	v_cndmask_b32_e64 v112, 0, v128, s[8:9]
	v_add_f32_e32 v109, v109, v112
	v_cndmask_b32_e64 v113, 0, v132, s[10:11]
	s_waitcnt lgkmcnt(2)
	v_mov_b32_e32 v112, v136
	v_pk_add_f32 v[108:109], v[108:109], v[112:113]
	s_waitcnt lgkmcnt(1)
	v_mov_b32_e32 v127, v142
	v_pk_add_f32 v[108:109], v[126:127], v[108:109]
	v_cndmask_b32_e64 v127, 0, v133, s[10:11]
	v_sub_f32_e32 v108, v108, v109
	v_mul_f32_e32 v108, 0x3fb8aa3b, v108
	v_mul_f32_e32 v104, 0x3fb8aa3b, v109
	v_mul_f32_e32 v110, 0xbfb8aa3b, v109
	v_exp_f32_e32 v128, v108
	v_cndmask_b32_e64 v108, v105, 0, s[0:1]
	v_cndmask_b32_e64 v109, 0, v129, s[8:9]
	v_add_f32_e32 v109, v108, v109
	v_mov_b32_e32 v108, v133
	v_mov_b32_e32 v126, v137
	v_add_f32_e32 v142, v105, v129
	v_pk_add_f32 v[108:109], v[108:109], v[126:127]
	s_waitcnt vmcnt(7)
	v_lshlrev_b32_e32 v126, 16, v94
	v_pk_add_f32 v[108:109], v[142:143], v[108:109]
	v_and_b32_e32 v127, 0xffff0000, v94
	v_mul_f32_e32 v94, 0xbfb8aa3b, v109
	v_exp_f32_e32 v112, v110
	v_mul_f32_e32 v105, 0x3fb8aa3b, v109
	v_exp_f32_e32 v113, v94
	v_exp_f32_e32 v104, v104
	v_exp_f32_e32 v105, v105
	s_waitcnt vmcnt(6)
	v_lshlrev_b32_e32 v140, 16, v90
	v_and_b32_e32 v141, 0xffff0000, v90
	v_sub_f32_e32 v90, v108, v109
	v_mul_f32_e32 v90, 0x3fb8aa3b, v90
	v_exp_f32_e32 v142, v90
	v_cndmask_b32_e64 v90, v106, 0, s[0:1]
	v_cndmask_b32_e64 v94, 0, v130, s[8:9]
	v_pk_mul_f32 v[182:183], v[112:113], v[140:141]
	v_add_f32_e32 v109, v90, v94
	v_cndmask_b32_e64 v113, 0, v134, s[10:11]
	v_mov_b32_e32 v108, v134
	v_mov_b32_e32 v112, v138
	v_pk_mul_f32 v[104:105], v[104:105], v[126:127]
	v_add_f32_e32 v126, v106, v130
	v_pk_add_f32 v[108:109], v[108:109], v[112:113]
	v_mov_b32_e32 v127, v144
	v_pk_add_f32 v[108:109], v[126:127], v[108:109]
	v_cndmask_b32_e64 v113, 0, v135, s[10:11]
	v_mul_f32_e32 v90, 0x3fb8aa3b, v109
	v_exp_f32_e32 v106, v90
	v_mul_f32_e32 v90, 0xbfb8aa3b, v109
	v_exp_f32_e32 v94, v90
	v_sub_f32_e32 v90, v108, v109
	v_mul_f32_e32 v90, 0x3fb8aa3b, v90
	v_exp_f32_e32 v126, v90
	v_cndmask_b32_e64 v90, v107, 0, s[0:1]
	v_cndmask_b32_e64 v108, 0, v131, s[8:9]
	v_add_f32_e32 v109, v90, v108
	v_mov_b32_e32 v108, v135
	v_mov_b32_e32 v112, v139
	v_add_f32_e32 v144, v107, v131
	v_pk_add_f32 v[108:109], v[108:109], v[112:113]
	ds_read_b128 v[166:169], v111 offset:528
	ds_read_b128 v[170:173], v111 offset:1040
	v_pk_add_f32 v[108:109], v[144:145], v[108:109]
	ds_read_b128 v[174:177], v111 offset:1552
	v_mul_f32_e32 v90, 0x3fb8aa3b, v109
	v_exp_f32_e32 v107, v90
	v_mul_f32_e32 v90, 0xbfb8aa3b, v109
	v_lshlrev_b32_e32 v112, 16, v95
	v_and_b32_e32 v113, 0xffff0000, v95
	v_exp_f32_e32 v95, v90
	v_sub_f32_e32 v90, v108, v109
	v_mul_f32_e32 v90, 0x3fb8aa3b, v90
	v_lshlrev_b32_e32 v134, 16, v91
	v_and_b32_e32 v135, 0xffff0000, v91
	v_exp_f32_e32 v138, v90
	v_cndmask_b32_e64 v90, v98, 0, s[0:1]
	s_waitcnt lgkmcnt(2)
	v_cndmask_b32_e64 v91, 0, v166, s[8:9]
	v_add_f32_e32 v91, v90, v91
	s_waitcnt lgkmcnt(1)
	v_cndmask_b32_e64 v109, 0, v170, s[10:11]
	v_mov_b32_e32 v90, v170
	s_waitcnt lgkmcnt(0)
	v_mov_b32_e32 v108, v174
	v_pk_mul_f32 v[106:107], v[106:107], v[112:113]
	v_add_f32_e32 v112, v98, v166
	v_pk_add_f32 v[90:91], v[90:91], v[108:109]
	v_mov_b32_e32 v113, v178
	v_pk_add_f32 v[90:91], v[112:113], v[90:91]
	v_cndmask_b32_e64 v131, 0, v171, s[10:11]
	v_sub_f32_e32 v90, v90, v91
	v_mul_f32_e32 v90, 0x3fb8aa3b, v90
	v_mul_f32_e32 v98, 0x3fb8aa3b, v91
	v_mul_f32_e32 v108, 0xbfb8aa3b, v91
	v_exp_f32_e32 v112, v90
	v_cndmask_b32_e64 v90, v99, 0, s[0:1]
	v_cndmask_b32_e64 v91, 0, v167, s[8:9]
	v_add_f32_e32 v91, v90, v91
	v_mov_b32_e32 v90, v171
	v_mov_b32_e32 v130, v175
	v_add_f32_e32 v178, v99, v167
	v_pk_add_f32 v[90:91], v[90:91], v[130:131]
	v_exp_f32_e32 v98, v98
	v_pk_add_f32 v[90:91], v[178:179], v[90:91]
	v_lshlrev_b32_e32 v130, 16, v96
	v_mul_f32_e32 v99, 0x3fb8aa3b, v91
	v_exp_f32_e32 v99, v99
	v_sub_f32_e32 v90, v90, v91
	v_mul_f32_e32 v90, 0x3fb8aa3b, v90
	v_and_b32_e32 v131, 0xffff0000, v96
	v_mul_f32_e32 v96, 0xbfb8aa3b, v91
	v_exp_f32_e32 v146, v90
	v_cndmask_b32_e64 v90, v100, 0, s[0:1]
	v_cndmask_b32_e64 v91, 0, v168, s[8:9]
	v_pk_mul_f32 v[98:99], v[98:99], v[130:131]
	v_add_f32_e32 v91, v90, v91
	v_cndmask_b32_e64 v131, 0, v172, s[10:11]
	v_mov_b32_e32 v90, v172
	v_mov_b32_e32 v130, v176
	v_add_f32_e32 v132, v100, v168
	v_pk_add_f32 v[90:91], v[90:91], v[130:131]
	v_mov_b32_e32 v133, v180
	v_pk_add_f32 v[90:91], v[132:133], v[90:91]
	v_lshlrev_b32_e32 v144, 16, v92
	v_sub_f32_e32 v90, v90, v91
	v_and_b32_e32 v145, 0xffff0000, v92
	v_mul_f32_e32 v92, 0x3fb8aa3b, v91
	v_mul_f32_e32 v90, 0x3fb8aa3b, v90
	v_exp_f32_e32 v100, v92
	v_mul_f32_e32 v92, 0xbfb8aa3b, v91
	v_exp_f32_e32 v110, v90
	v_cndmask_b32_e64 v90, v101, 0, s[0:1]
	v_cndmask_b32_e64 v91, 0, v169, s[8:9]
	v_add_f32_e32 v91, v90, v91
	v_cndmask_b32_e64 v131, 0, v173, s[10:11]
	v_mov_b32_e32 v90, v173
	v_mov_b32_e32 v130, v177
	v_add_f32_e32 v180, v101, v169
	v_pk_add_f32 v[90:91], v[90:91], v[130:131]
	v_exp_f32_e32 v109, v96
	v_pk_add_f32 v[90:91], v[180:181], v[90:91]
	v_exp_f32_e32 v96, v92
	v_mul_f32_e32 v92, 0x3fb8aa3b, v91
	v_exp_f32_e32 v101, v92
	v_mul_f32_e32 v92, 0xbfb8aa3b, v91
	v_exp_f32_e32 v108, v108
	v_lshlrev_b32_e32 v130, 16, v97
	v_and_b32_e32 v131, 0xffff0000, v97
	v_exp_f32_e32 v97, v92
	v_lshlrev_b32_e32 v147, 1, v156
	v_and_b32_e32 v165, 32, v124
	v_sub_f32_e32 v90, v90, v91
	v_cvt_pk_bf16_f32 v92, v98, v99
	v_and_or_b32 v98, v147, 30, v165
	v_lshl_add_u32 v164, v160, 4, 0
	v_pk_mul_f32 v[100:101], v[100:101], v[130:131]
	v_lshlrev_b32_e32 v130, 16, v93
	v_and_b32_e32 v131, 0xffff0000, v93
	v_mul_f32_e32 v90, 0x3fb8aa3b, v90
	v_lshl_add_u64 v[132:133], s[56:57], 0, v[102:103]
	v_lshlrev_b32_e32 v114, 4, v98
	v_pk_mul_f32 v[94:95], v[94:95], v[134:135]
	v_pk_mul_f32 v[108:109], v[108:109], v[144:145]
	v_pk_mul_f32 v[96:97], v[96:97], v[130:131]
	v_exp_f32_e32 v136, v90
	v_cvt_pk_bf16_f32 v90, v104, v105
	v_cvt_pk_bf16_f32 v91, v106, v107
	v_cvt_pk_bf16_f32 v93, v100, v101
	v_mad_u32_u24 v100, v156, s83, v164
	v_lshl_add_u64 v[98:99], v[132:133], 0, v[114:115]
	ds_write_b128 v100, v[90:93]
	global_store_dwordx4 v[98:99], v[90:93], off sc1
	v_or_b32_e32 v114, 1, v147
	v_mul_u32_u24_e32 v113, 0x204, v114
	v_cvt_pk_bf16_f32 v90, v182, v183
	v_cvt_pk_bf16_f32 v91, v94, v95
	v_cvt_pk_bf16_f32 v92, v108, v109
	v_cvt_pk_bf16_f32 v93, v96, v97
	ds_write_b128 v100, v[90:93] offset:17408
	ds_read_b128 v[94:97], v111
	ds_read_b128 v[90:93], v111 offset:16
	ds_read_b128 v[98:101], v111 offset:512
	ds_read_b128 v[102:105], v111 offset:1024
	ds_read_b128 v[106:109], v111 offset:1536
	s_waitcnt lgkmcnt(4)
	v_cndmask_b32_e64 v127, v94, 0, s[0:1]
	ds_read_b128 v[166:169], v111 offset:528
	s_waitcnt lgkmcnt(3)
	v_add_f32_e32 v182, v94, v98
	v_add3_u32 v94, s18, v113, v184
	ds_read2_b32 v[184:185], v94 offset1:1
	v_cndmask_b32_e64 v129, 0, v98, s[8:9]
	v_add_f32_e32 v179, v127, v129
	s_waitcnt lgkmcnt(3)
	v_cndmask_b32_e64 v181, 0, v102, s[10:11]
	v_mov_b32_e32 v178, v102
	s_waitcnt lgkmcnt(2)
	v_mov_b32_e32 v180, v106
	v_pk_add_f32 v[178:179], v[178:179], v[180:181]
	s_waitcnt lgkmcnt(0)
	v_mov_b32_e32 v183, v184
	v_pk_add_f32 v[178:179], v[182:183], v[178:179]
	v_cndmask_b32_e64 v106, 0, v99, s[8:9]
	v_sub_f32_e32 v102, v178, v179
	v_mul_f32_e32 v102, 0x3fb8aa3b, v102
	v_exp_f32_e32 v129, v102
	v_cndmask_b32_e64 v102, v95, 0, s[0:1]
	ds_read_b128 v[170:173], v111 offset:1040
	ds_read_b128 v[174:177], v111 offset:1552
	ds_read2_b32 v[180:181], v94 offset0:2 offset1:3
	ds_read2_b32 v[186:187], v94 offset0:4 offset1:5
	ds_read2_b32 v[188:189], v94 offset0:6 offset1:7
	v_mul_f32_e32 v94, 0x3fb8aa3b, v179
	v_mul_f32_e32 v98, 0xbfb8aa3b, v179
	v_add_f32_e32 v179, v102, v106
	v_cndmask_b32_e64 v183, 0, v103, s[10:11]
	v_mov_b32_e32 v178, v103
	v_mov_b32_e32 v182, v107
	v_add_f32_e32 v184, v95, v99
	v_pk_add_f32 v[102:103], v[178:179], v[182:183]
	v_exp_f32_e32 v94, v94
	v_pk_add_f32 v[102:103], v[184:185], v[102:103]
	s_waitcnt vmcnt(6)
	v_lshlrev_b32_e32 v106, 16, v86
	v_mul_f32_e32 v95, 0x3fb8aa3b, v103
	v_exp_f32_e32 v95, v95
	v_and_b32_e32 v107, 0xffff0000, v86
	v_mul_f32_e32 v86, 0xbfb8aa3b, v103
	v_exp_f32_e32 v98, v98
	v_pk_mul_f32 v[94:95], v[94:95], v[106:107]
	s_waitcnt vmcnt(5)
	v_lshlrev_b32_e32 v106, 16, v82
	v_and_b32_e32 v107, 0xffff0000, v82
	v_sub_f32_e32 v82, v102, v103
	v_exp_f32_e32 v99, v86
	v_mul_f32_e32 v82, 0x3fb8aa3b, v82
	v_exp_f32_e32 v143, v82
	v_mov_b32_e32 v178, v140
	v_mov_b32_e32 v179, v106
	v_cndmask_b32_e64 v82, v96, 0, s[0:1]
	v_cndmask_b32_e64 v86, 0, v100, s[8:9]
	v_pk_mul_f32 v[98:99], v[98:99], v[106:107]
	v_pk_mul_f32 v[102:103], v[128:129], v[178:179]
	v_mov_b32_e32 v106, v141
	v_add_f32_e32 v129, v82, v86
	v_cndmask_b32_e64 v141, 0, v104, s[10:11]
	v_mov_b32_e32 v128, v104
	v_mov_b32_e32 v140, v108
	v_pk_mul_f32 v[106:107], v[142:143], v[106:107]
	v_add_f32_e32 v142, v96, v100
	v_pk_add_f32 v[128:129], v[128:129], v[140:141]
	s_waitcnt lgkmcnt(2)
	v_mov_b32_e32 v143, v180
	v_pk_add_f32 v[128:129], v[142:143], v[128:129]
	v_cndmask_b32_e64 v100, 0, v101, s[8:9]
	v_mul_f32_e32 v82, 0x3fb8aa3b, v129
	v_exp_f32_e32 v96, v82
	v_mul_f32_e32 v82, 0xbfb8aa3b, v129
	v_exp_f32_e32 v86, v82
	v_sub_f32_e32 v82, v128, v129
	v_mul_f32_e32 v82, 0x3fb8aa3b, v82
	v_exp_f32_e32 v127, v82
	v_cndmask_b32_e64 v82, v97, 0, s[0:1]
	v_add_f32_e32 v129, v82, v100
	v_cndmask_b32_e64 v141, 0, v105, s[10:11]
	v_mov_b32_e32 v128, v105
	v_mov_b32_e32 v140, v109
	v_add_f32_e32 v180, v97, v101
	v_pk_add_f32 v[100:101], v[128:129], v[140:141]
	v_lshlrev_b32_e32 v104, 16, v87
	v_pk_add_f32 v[100:101], v[180:181], v[100:101]
	v_and_b32_e32 v105, 0xffff0000, v87
	v_mul_f32_e32 v82, 0x3fb8aa3b, v101
	v_exp_f32_e32 v97, v82
	v_mul_f32_e32 v82, 0xbfb8aa3b, v101
	v_sub_f32_e32 v100, v100, v101
	v_exp_f32_e32 v87, v82
	v_mul_f32_e32 v100, 0x3fb8aa3b, v100
	v_exp_f32_e32 v139, v100
	v_lshlrev_b32_e32 v82, 16, v83
	v_and_b32_e32 v83, 0xffff0000, v83
	v_pk_mul_f32 v[96:97], v[96:97], v[104:105]
	v_pk_mul_f32 v[86:87], v[86:87], v[82:83]
	v_mov_b32_e32 v104, v134
	v_mov_b32_e32 v105, v82
	v_mov_b32_e32 v82, v135
	v_pk_mul_f32 v[100:101], v[126:127], v[104:105]
	v_pk_mul_f32 v[104:105], v[138:139], v[82:83]
	v_cndmask_b32_e64 v82, v90, 0, s[0:1]
	v_cndmask_b32_e64 v83, 0, v166, s[8:9]
	v_add_f32_e32 v83, v82, v83
	v_cndmask_b32_e64 v109, 0, v170, s[10:11]
	v_mov_b32_e32 v82, v170
	v_mov_b32_e32 v108, v174
	v_add_f32_e32 v126, v90, v166
	v_pk_add_f32 v[82:83], v[82:83], v[108:109]
	s_waitcnt lgkmcnt(1)
	v_mov_b32_e32 v127, v186
	v_pk_add_f32 v[82:83], v[126:127], v[82:83]
	v_cndmask_b32_e64 v127, 0, v171, s[10:11]
	v_sub_f32_e32 v82, v82, v83
	v_mul_f32_e32 v82, 0x3fb8aa3b, v82
	v_mul_f32_e32 v90, 0x3fb8aa3b, v83
	v_mul_f32_e32 v108, 0xbfb8aa3b, v83
	v_exp_f32_e32 v113, v82
	v_cndmask_b32_e64 v82, v91, 0, s[0:1]
	v_cndmask_b32_e64 v83, 0, v167, s[8:9]
	v_add_f32_e32 v83, v82, v83
	v_mov_b32_e32 v82, v171
	v_mov_b32_e32 v126, v175
	v_add_f32_e32 v186, v91, v167
	v_pk_add_f32 v[82:83], v[82:83], v[126:127]
	v_exp_f32_e32 v90, v90
	v_pk_add_f32 v[82:83], v[186:187], v[82:83]
	v_lshlrev_b32_e32 v126, 16, v88
	v_mul_f32_e32 v91, 0x3fb8aa3b, v83
	v_exp_f32_e32 v91, v91
	v_and_b32_e32 v127, 0xffff0000, v88
	v_sub_f32_e32 v82, v82, v83
	v_mul_f32_e32 v82, 0x3fb8aa3b, v82
	v_pk_mul_f32 v[90:91], v[90:91], v[126:127]
	v_lshlrev_b32_e32 v126, 16, v84
	v_and_b32_e32 v161, 50, v147
	v_mul_f32_e32 v88, 0xbfb8aa3b, v83
	v_mov_b32_e32 v128, v144
	v_exp_f32_e32 v147, v82
	v_mov_b32_e32 v129, v126
	v_cndmask_b32_e64 v82, v92, 0, s[0:1]
	v_cndmask_b32_e64 v83, 0, v168, s[8:9]
	v_pk_mul_f32 v[112:113], v[112:113], v[128:129]
	v_add_f32_e32 v83, v82, v83
	v_cndmask_b32_e64 v129, 0, v172, s[10:11]
	v_mov_b32_e32 v82, v172
	v_mov_b32_e32 v128, v176
	v_add_f32_e32 v134, v92, v168
	v_pk_add_f32 v[82:83], v[82:83], v[128:129]
	s_waitcnt lgkmcnt(0)
	v_mov_b32_e32 v135, v188
	v_pk_add_f32 v[82:83], v[134:135], v[82:83]
	v_and_b32_e32 v127, 0xffff0000, v84
	v_sub_f32_e32 v82, v82, v83
	v_mul_f32_e32 v84, 0x3fb8aa3b, v83
	v_mul_f32_e32 v82, 0x3fb8aa3b, v82
	v_exp_f32_e32 v92, v84
	v_mul_f32_e32 v84, 0xbfb8aa3b, v83
	v_exp_f32_e32 v111, v82
	v_cndmask_b32_e64 v82, v93, 0, s[0:1]
	v_cndmask_b32_e64 v83, 0, v169, s[8:9]
	v_add_f32_e32 v83, v82, v83
	v_cndmask_b32_e64 v129, 0, v173, s[10:11]
	v_mov_b32_e32 v82, v173
	v_mov_b32_e32 v128, v177
	v_add_f32_e32 v188, v93, v169
	v_pk_add_f32 v[82:83], v[82:83], v[128:129]
	v_exp_f32_e32 v109, v88
	v_pk_add_f32 v[82:83], v[188:189], v[82:83]
	v_exp_f32_e32 v88, v84
	v_mul_f32_e32 v84, 0x3fb8aa3b, v83
	v_exp_f32_e32 v93, v84
	v_mul_f32_e32 v84, 0xbfb8aa3b, v83
	v_sub_f32_e32 v82, v82, v83
	v_lshlrev_b32_e32 v128, 16, v89
	v_and_b32_e32 v129, 0xffff0000, v89
	v_exp_f32_e32 v89, v84
	v_mul_f32_e32 v82, 0x3fb8aa3b, v82
	v_exp_f32_e32 v137, v82
	v_exp_f32_e32 v108, v108
	v_lshlrev_b32_e32 v84, 16, v85
	v_and_b32_e32 v85, 0xffff0000, v85
	v_pk_mul_f32 v[92:93], v[92:93], v[128:129]
	v_pk_mul_f32 v[88:89], v[88:89], v[84:85]
	v_mov_b32_e32 v128, v130
	v_mov_b32_e32 v129, v84
	v_mov_b32_e32 v84, v131
	v_pk_mul_f32 v[110:111], v[110:111], v[128:129]
	v_pk_mul_f32 v[128:129], v[136:137], v[84:85]
	v_cvt_pk_bf16_f32 v84, v90, v91
	v_and_or_b32 v90, v114, 31, v165
	v_cvt_pk_bf16_f32 v85, v92, v93
	v_mad_u32_u24 v92, v114, s84, v164
	v_lshlrev_b32_e32 v114, 4, v90
	v_pk_mul_f32 v[108:109], v[108:109], v[126:127]
	v_cvt_pk_bf16_f32 v82, v94, v95
	v_cvt_pk_bf16_f32 v83, v96, v97
	v_lshl_add_u64 v[90:91], v[132:133], 0, v[114:115]
	v_lshlrev_b32_e32 v162, 2, v124
	ds_write_b128 v92, v[82:85]
	global_store_dwordx4 v[90:91], v[82:85], off sc1
	v_and_b32_e32 v163, 4, v124
	v_mov_b32_e32 v126, v145
	v_cvt_pk_bf16_f32 v82, v98, v99
	v_cvt_pk_bf16_f32 v83, v86, v87
	v_cvt_pk_bf16_f32 v84, v108, v109
	v_cvt_pk_bf16_f32 v85, v88, v89
	ds_write_b128 v92, v[82:85] offset:17408
	v_and_b32_e32 v82, 8, v162
	v_or3_b32 v82, v161, v163, v82
	v_lshlrev_b32_e32 v82, 1, v82
	v_mul_lo_u32 v83, v160, s85
	v_add3_u32 v85, 0, v82, v83
	v_cvt_pk_bf16_f32 v84, v102, v103
	v_cvt_pk_bf16_f32 v86, v106, v107
	v_add_u32_e32 v85, 0x8800, v85
	v_pk_mul_f32 v[126:127], v[146:147], v[126:127]
	ds_write2_b32 v85, v84, v86 offset1:36
	v_cvt_pk_bf16_f32 v84, v100, v101
	v_cvt_pk_bf16_f32 v86, v104, v105
	ds_write2_b32 v85, v84, v86 offset0:72 offset1:108
	v_cvt_pk_bf16_f32 v84, v112, v113
	v_cvt_pk_bf16_f32 v86, v126, v127
	ds_write2_b32 v85, v84, v86 offset0:144 offset1:180
	v_cvt_pk_bf16_f32 v84, v110, v111
	v_cvt_pk_bf16_f32 v86, v128, v129
	ds_write2_b32 v85, v84, v86 offset0:216 offset1:252
	s_and_saveexec_b64 s[0:1], vcc
	s_cbranch_execz .LBB0_1096
	ds_read2st64_b32 v[84:85], v159 offset1:2
	ds_read2st64_b32 v[86:87], v159 offset0:4 offset1:6
	s_lshl_b64 s[8:9], s[48:49], 9
	s_add_u32 s8, s79, s8
	s_addc_u32 s9, s80, s9
	s_waitcnt lgkmcnt(1)
	v_mov_b32_e32 v88, v84
	s_waitcnt lgkmcnt(0)
	v_mov_b32_e32 v89, v86
	v_mov_b32_e32 v86, v85
	v_pk_add_f32 v[84:85], v[88:89], v[86:87]
	s_nop 0
	v_add_f32_e32 v84, v84, v85
	v_mul_f32_e32 v84, 0x3fb8aa3b, v84
	v_exp_f32_e32 v86, v84
	v_lshl_add_u64 v[84:85], v[124:125], 2, s[8:9]
	global_store_dword v[84:85], v148, off
	v_add_u32_e32 v84, 0x18b00, v157
	v_mul_f32_e32 v148, v148, v86
	ds_write_b32 v84, v86
